# v87: mLSTM state pass, third chunk-loop copy: the four K^T fragment loads issued together with counted waits instead of one drained load at a time
# speedup vs baseline: 1.0122x; 1.0037x over previous
.LBB0_338:
	v_sub_f32_e32 v47, s45, v50
	s_waitcnt vmcnt(0)
	v_add_f32_e32 v46, v46, v47
	v_sub_f32_e32 v47, s45, v51
	v_add_f32_e32 v0, v0, v47
	v_max_f32_e32 v47, v46, v0
	ds_bpermute_b32 v48, v117, v47
	v_add_f32_e32 v49, s45, v102
	s_ashr_i32 s45, s44, 31
	s_lshl_b64 s[44:45], s[44:45], 1
	s_add_u32 s44, s46, s44
	s_waitcnt lgkmcnt(0)
	v_max_f32_e32 v48, v48, v48
	v_max_f32_e32 v47, v47, v48
	ds_bpermute_b32 v48, v118, v47
	s_addc_u32 s45, s47, s45
	s_waitcnt lgkmcnt(0)
	v_max_f32_e32 v48, v48, v48
	v_max_f32_e32 v47, v47, v48
	ds_bpermute_b32 v48, v119, v47
	s_waitcnt lgkmcnt(0)
	v_max_f32_e32 v48, v48, v48
	v_max_f32_e32 v47, v47, v48
	ds_bpermute_b32 v48, v120, v47
	s_waitcnt lgkmcnt(0)
	v_max_f32_e32 v48, v48, v48
	v_max_f32_e32 v47, v47, v48
	ds_bpermute_b32 v48, v121, v47
	s_waitcnt lgkmcnt(0)
	v_max_f32_e32 v48, v48, v48
	v_max_f32_e32 v47, v47, v48
	ds_bpermute_b32 v48, v122, v47
	s_waitcnt lgkmcnt(0)
	v_max3_f32 v102, v49, v47, v48
	v_sub_f32_e32 v0, v0, v102
	v_sub_f32_e32 v46, v46, v102
	v_mul_f32_e32 v0, 0x3fb8aa3b, v0
	v_mul_f32_e32 v46, 0x3fb8aa3b, v46
	v_exp_f32_e32 v47, v0
	v_sub_f32_e32 v0, v49, v102
	v_exp_f32_e32 v46, v46
	v_mul_f32_e32 v0, 0x3fb8aa3b, v0
	v_exp_f32_e32 v0, v0
	ds_write_b64 v123, v[46:47]
	v_pk_mul_f32 v[48:49], v[44:45], v[0:1] op_sel_hi:[1,0]
	v_pk_mul_f32 v[46:47], v[42:43], v[0:1] op_sel_hi:[1,0]
	v_pk_mul_f32 v[44:45], v[56:57], v[0:1] op_sel_hi:[1,0]
	v_pk_mul_f32 v[42:43], v[54:55], v[0:1] op_sel_hi:[1,0]
	ds_read_b128 v[50:53], v126
	ds_read_b128 v[54:57], v126 offset:16
	global_load_dwordx4 v[180:183], v70, s[44:45]
	global_load_dwordx4 v[184:187], v70, s[44:45] offset:64
	global_load_dwordx4 v[188:191], v70, s[44:45] offset:128
	global_load_dwordx4 v[192:195], v70, s[44:45] offset:192
	v_pk_mul_f32 v[40:41], v[40:41], v[0:1] op_sel_hi:[1,0]
	v_pk_mul_f32 v[38:39], v[38:39], v[0:1] op_sel_hi:[1,0]
	v_pk_mul_f32 v[36:37], v[36:37], v[0:1] op_sel_hi:[1,0]
	v_pk_mul_f32 v[34:35], v[34:35], v[0:1] op_sel_hi:[1,0]
	v_pk_mul_f32 v[32:33], v[32:33], v[0:1] op_sel_hi:[1,0]
	v_pk_mul_f32 v[30:31], v[30:31], v[0:1] op_sel_hi:[1,0]
	v_pk_mul_f32 v[28:29], v[28:29], v[0:1] op_sel_hi:[1,0]
	v_pk_mul_f32 v[26:27], v[26:27], v[0:1] op_sel_hi:[1,0]
	v_pk_mul_f32 v[24:25], v[24:25], v[0:1] op_sel_hi:[1,0]
	v_pk_mul_f32 v[22:23], v[22:23], v[0:1] op_sel_hi:[1,0]
	v_pk_mul_f32 v[20:21], v[20:21], v[0:1] op_sel_hi:[1,0]
	v_pk_mul_f32 v[18:19], v[18:19], v[0:1] op_sel_hi:[1,0]
	s_waitcnt vmcnt(3)
	v_mov_b32_e32 v58, v180
	v_mov_b32_e32 v59, v181
	v_mov_b32_e32 v60, v182
	v_mov_b32_e32 v61, v183
	v_lshlrev_b32_e32 v62, 16, v58
	v_and_b32_e32 v63, 0xffff0000, v58
	v_lshlrev_b32_e32 v58, 16, v59
	v_and_b32_e32 v59, 0xffff0000, v59
	s_waitcnt lgkmcnt(1)
	v_pk_mul_f32 v[52:53], v[52:53], v[58:59]
	v_lshlrev_b32_e32 v58, 16, v60
	v_and_b32_e32 v59, 0xffff0000, v60
	v_pk_mul_f32 v[50:51], v[50:51], v[62:63]
	s_waitcnt lgkmcnt(0)
	v_pk_mul_f32 v[54:55], v[54:55], v[58:59]
	v_lshlrev_b32_e32 v58, 16, v61
	v_and_b32_e32 v59, 0xffff0000, v61
	v_pk_mul_f32 v[56:57], v[56:57], v[58:59]
	v_mov_b32_e32 v58, v50
	v_mov_b32_e32 v59, v54
	v_mov_b32_e32 v60, v51
	v_mov_b32_e32 v61, v55
	v_pk_add_f32 v[58:59], v[58:59], v[60:61]
	v_mov_b32_e32 v60, v52
	v_mov_b32_e32 v61, v56
	v_mov_b32_e32 v62, v53
	v_mov_b32_e32 v63, v57
	v_pk_add_f32 v[60:61], v[60:61], v[62:63]
	v_cvt_pk_bf16_f32 v50, v50, v51
	v_pk_add_f32 v[58:59], v[58:59], v[60:61]
	v_cvt_pk_bf16_f32 v51, v52, v53
	v_pk_add_f32 v[80:81], v[58:59], v[58:59] op_sel:[0,1] op_sel_hi:[1,0]
	v_cvt_pk_bf16_f32 v52, v54, v55
	v_cvt_pk_bf16_f32 v53, v56, v57
	ds_read_b128 v[54:57], v126 offset:128
	ds_read_b128 v[58:61], v126 offset:144
	s_waitcnt vmcnt(2)
	v_mov_b32_e32 v62, v184
	v_mov_b32_e32 v63, v185
	v_mov_b32_e32 v64, v186
	v_mov_b32_e32 v65, v187
	v_lshlrev_b32_e32 v66, 16, v62
	v_and_b32_e32 v67, 0xffff0000, v62
	v_lshlrev_b32_e32 v62, 16, v63
	v_and_b32_e32 v63, 0xffff0000, v63
	s_waitcnt lgkmcnt(1)
	v_pk_mul_f32 v[56:57], v[56:57], v[62:63]
	v_lshlrev_b32_e32 v62, 16, v64
	v_and_b32_e32 v63, 0xffff0000, v64
	v_pk_mul_f32 v[54:55], v[54:55], v[66:67]
	s_waitcnt lgkmcnt(0)
	v_pk_mul_f32 v[62:63], v[58:59], v[62:63]
	v_lshlrev_b32_e32 v58, 16, v65
	v_and_b32_e32 v59, 0xffff0000, v65
	v_pk_mul_f32 v[64:65], v[60:61], v[58:59]
	v_mov_b32_e32 v58, v54
	v_mov_b32_e32 v59, v56
	v_mov_b32_e32 v60, v55
	v_mov_b32_e32 v61, v57
	v_pk_add_f32 v[58:59], v[58:59], v[60:61]
	v_mov_b32_e32 v60, v63
	v_pk_add_f32 v[82:83], v[58:59], v[58:59] op_sel:[0,1] op_sel_hi:[1,0]
	v_mov_b32_e32 v58, v62
	v_mov_b32_e32 v59, v64
	v_mov_b32_e32 v61, v65
	v_pk_add_f32 v[58:59], v[58:59], v[60:61]
	v_cvt_pk_bf16_f32 v60, v62, v63
	v_pk_add_f32 v[84:85], v[58:59], v[58:59] op_sel:[0,1] op_sel_hi:[1,0]
	v_cvt_pk_bf16_f32 v58, v54, v55
	v_cvt_pk_bf16_f32 v59, v56, v57
	v_cvt_pk_bf16_f32 v61, v64, v65
	ds_read_b128 v[62:65], v126 offset:256
	ds_read_b128 v[54:57], v126 offset:272
	s_waitcnt vmcnt(1)
	v_mov_b32_e32 v66, v188
	v_mov_b32_e32 v67, v189
	v_mov_b32_e32 v68, v190
	v_mov_b32_e32 v69, v191
	v_lshlrev_b32_e32 v72, 16, v66
	v_and_b32_e32 v73, 0xffff0000, v66
	v_lshlrev_b32_e32 v66, 16, v67
	v_and_b32_e32 v67, 0xffff0000, v67
	v_lshlrev_b32_e32 v86, 16, v68
	v_and_b32_e32 v87, 0xffff0000, v68
	v_lshlrev_b32_e32 v68, 16, v69
	v_and_b32_e32 v69, 0xffff0000, v69
	s_waitcnt lgkmcnt(1)
	v_pk_mul_f32 v[94:95], v[62:63], v[72:73]
	v_pk_mul_f32 v[96:97], v[64:65], v[66:67]
	s_waitcnt lgkmcnt(0)
	v_pk_mul_f32 v[98:99], v[54:55], v[86:87]
	v_pk_mul_f32 v[128:129], v[56:57], v[68:69]
	v_pk_fma_f32 v[90:91], v[62:63], v[72:73], v[94:95] op_sel:[0,0,1] op_sel_hi:[1,1,0]
	v_pk_fma_f32 v[92:93], v[64:65], v[66:67], v[96:97] op_sel:[0,0,1] op_sel_hi:[1,1,0]
	v_pk_fma_f32 v[86:87], v[54:55], v[86:87], v[98:99] op_sel:[0,0,1] op_sel_hi:[1,1,0]
	v_pk_fma_f32 v[88:89], v[56:57], v[68:69], v[128:129] op_sel:[0,0,1] op_sel_hi:[1,1,0]
	ds_read_b128 v[66:69], v126 offset:384
	ds_read_b128 v[54:57], v126 offset:400
	v_cvt_pk_bf16_f32 v62, v94, v95
	v_cvt_pk_bf16_f32 v64, v98, v99
	v_cvt_pk_bf16_f32 v63, v96, v97
	v_cvt_pk_bf16_f32 v65, v128, v129
	s_waitcnt vmcnt(0)
	v_mov_b32_e32 v70, v192
	v_mov_b32_e32 v71, v193
	v_mov_b32_e32 v72, v194
	v_mov_b32_e32 v73, v195
	v_lshlrev_b32_e32 v94, 16, v70
	v_and_b32_e32 v95, 0xffff0000, v70
	s_waitcnt lgkmcnt(1)
	v_pk_mul_f32 v[94:95], v[66:67], v[94:95]
	v_lshlrev_b32_e32 v66, 16, v71
	v_and_b32_e32 v67, 0xffff0000, v71
	v_pk_mul_f32 v[98:99], v[68:69], v[66:67]
	v_lshlrev_b32_e32 v66, 16, v72
	v_and_b32_e32 v67, 0xffff0000, v72
	s_waitcnt lgkmcnt(0)
	v_pk_mul_f32 v[96:97], v[54:55], v[66:67]
	v_lshlrev_b32_e32 v54, 16, v73
	v_and_b32_e32 v55, 0xffff0000, v73
	v_pk_mul_f32 v[70:71], v[56:57], v[54:55]
	v_cvt_pk_bf16_f32 v66, v94, v95
	v_cvt_pk_bf16_f32 v67, v98, v99
	v_cvt_pk_bf16_f32 v68, v96, v97
	v_cvt_pk_bf16_f32 v69, v70, v71
	ds_read_b128 v[54:57], v125
	s_waitcnt lgkmcnt(0)
	v_mfma_f32_16x16x32_bf16 v[46:49], v[54:57], v[50:53], v[46:49]
	ds_read_b128 v[54:57], v125 offset:4352
	s_waitcnt lgkmcnt(0)
	v_mfma_f32_16x16x32_bf16 v[54:57], v[54:57], v[50:53], v[42:45]
	s_nop 2
	ds_read_b128 v[42:45], v125 offset:64
	s_waitcnt lgkmcnt(0)
	v_mfma_f32_16x16x32_bf16 v[42:45], v[42:45], v[58:61], v[46:49]
	s_nop 2
	ds_read_b128 v[46:49], v125 offset:128
	s_waitcnt lgkmcnt(0)
	v_mfma_f32_16x16x32_bf16 v[42:45], v[46:49], v[62:65], v[42:45]
	ds_read_b128 v[46:49], v125 offset:192
	s_waitcnt lgkmcnt(0)
	v_mfma_f32_16x16x32_bf16 v[42:45], v[46:49], v[66:69], v[42:45]
	ds_read_b128 v[46:49], v125 offset:4416
	s_waitcnt lgkmcnt(0)
	v_mfma_f32_16x16x32_bf16 v[46:49], v[46:49], v[58:61], v[54:57]
	s_nop 2
	ds_read_b128 v[54:57], v125 offset:4480
	s_waitcnt lgkmcnt(0)
	v_mfma_f32_16x16x32_bf16 v[46:49], v[54:57], v[62:65], v[46:49]
	ds_read_b128 v[54:57], v125 offset:4544
	s_waitcnt lgkmcnt(0)
	v_mfma_f32_16x16x32_bf16 v[54:57], v[54:57], v[66:69], v[46:49]
	s_nop 4
	ds_read_b128 v[46:49], v125 offset:8704
	s_waitcnt lgkmcnt(0)
	v_mfma_f32_16x16x32_bf16 v[38:41], v[46:49], v[50:53], v[38:41]
	ds_read_b128 v[46:49], v125 offset:8768
	s_waitcnt lgkmcnt(0)
	v_mfma_f32_16x16x32_bf16 v[38:41], v[46:49], v[58:61], v[38:41]
	ds_read_b128 v[46:49], v125 offset:8832
	s_waitcnt lgkmcnt(0)
	v_mfma_f32_16x16x32_bf16 v[38:41], v[46:49], v[62:65], v[38:41]
	ds_read_b128 v[46:49], v125 offset:8896
	s_waitcnt lgkmcnt(0)
	v_mfma_f32_16x16x32_bf16 v[38:41], v[46:49], v[66:69], v[38:41]
	ds_read_b128 v[46:49], v125 offset:13056
	s_waitcnt lgkmcnt(0)
	v_mfma_f32_16x16x32_bf16 v[34:37], v[46:49], v[50:53], v[34:37]
	ds_read_b128 v[46:49], v125 offset:13120
	s_waitcnt lgkmcnt(0)
	v_mfma_f32_16x16x32_bf16 v[34:37], v[46:49], v[58:61], v[34:37]
	ds_read_b128 v[46:49], v125 offset:13184
	s_waitcnt lgkmcnt(0)
	v_mfma_f32_16x16x32_bf16 v[34:37], v[46:49], v[62:65], v[34:37]
	ds_read_b128 v[46:49], v125 offset:13248
	s_waitcnt lgkmcnt(0)
	v_mfma_f32_16x16x32_bf16 v[34:37], v[46:49], v[66:69], v[34:37]
	ds_read_b128 v[46:49], v125 offset:17408
	v_mov_b32_e32 v91, v96
	v_mov_b32_e32 v93, v97
	v_mov_b32_e32 v87, v70
	v_mov_b32_e32 v89, v71
	v_mov_b32_e32 v83, v98
	v_mov_b32_e32 v85, v99
	v_mov_b32_e32 v81, v94
	v_mov_b32_e32 v94, v1
	s_waitcnt lgkmcnt(0)
	v_mfma_f32_16x16x32_bf16 v[30:33], v[46:49], v[50:53], v[30:33]
	ds_read_b128 v[46:49], v125 offset:17472
	s_waitcnt lgkmcnt(0)
	v_mfma_f32_16x16x32_bf16 v[30:33], v[46:49], v[58:61], v[30:33]
	ds_read_b128 v[46:49], v125 offset:17536
	s_waitcnt lgkmcnt(0)
	v_mfma_f32_16x16x32_bf16 v[30:33], v[46:49], v[62:65], v[30:33]
	ds_read_b128 v[46:49], v125 offset:17600
	s_waitcnt lgkmcnt(0)
	v_mfma_f32_16x16x32_bf16 v[30:33], v[46:49], v[66:69], v[30:33]
	ds_read_b128 v[46:49], v125 offset:21952
	ds_read_b128 v[128:131], v125 offset:21888
	ds_read_b128 v[132:135], v125 offset:21824
	ds_read_b128 v[136:139], v125 offset:21760
	s_waitcnt lgkmcnt(0)
	v_mfma_f32_16x16x32_bf16 v[26:29], v[136:139], v[50:53], v[26:29]
	v_mfma_f32_16x16x32_bf16 v[26:29], v[132:135], v[58:61], v[26:29]
	v_mfma_f32_16x16x32_bf16 v[26:29], v[128:131], v[62:65], v[26:29]
	v_mfma_f32_16x16x32_bf16 v[26:29], v[46:49], v[66:69], v[26:29]
	ds_read_b128 v[46:49], v125 offset:26304
	ds_read_b128 v[128:131], v125 offset:26240
	ds_read_b128 v[132:135], v125 offset:26176
	ds_read_b128 v[136:139], v125 offset:26112
	s_waitcnt lgkmcnt(0)
	v_mfma_f32_16x16x32_bf16 v[22:25], v[136:139], v[50:53], v[22:25]
	v_mfma_f32_16x16x32_bf16 v[22:25], v[132:135], v[58:61], v[22:25]
	v_mfma_f32_16x16x32_bf16 v[22:25], v[128:131], v[62:65], v[22:25]
	v_mfma_f32_16x16x32_bf16 v[22:25], v[46:49], v[66:69], v[22:25]
	ds_read_b128 v[46:49], v125 offset:30656
	ds_read_b128 v[128:131], v125 offset:30592
	ds_read_b128 v[132:135], v125 offset:30528
	ds_read_b128 v[136:139], v125 offset:30464
	s_waitcnt lgkmcnt(0)
	v_mfma_f32_16x16x32_bf16 v[18:21], v[136:139], v[50:53], v[18:21]
	v_add_f32_e64 v50, v86, v88
	v_add_f32_e64 v51, v87, v89
	v_mfma_f32_16x16x32_bf16 v[18:21], v[132:135], v[58:61], v[18:21]
	v_mfma_f32_16x16x32_bf16 v[18:21], v[128:131], v[62:65], v[18:21]
	v_mfma_f32_16x16x32_bf16 v[18:21], v[46:49], v[66:69], v[18:21]
	v_add_f32_e64 v48, v90, v92
	v_add_f32_e64 v49, v91, v93
	v_pk_add_f32 v[46:47], v[82:83], v[84:85]
	v_pk_add_f32 v[48:49], v[48:49], v[50:51]
	v_pk_add_f32 v[50:51], v[80:81], v[94:95]
	s_nop 0
	v_pk_add_f32 v[46:47], v[50:51], v[46:47]
	s_nop 0
	v_pk_add_f32 v[46:47], v[46:47], v[48:49]
	s_nop 0
	v_add_f32_e32 v46, v46, v47
	ds_bpermute_b32 v47, v121, v46
	s_mov_b64 s[44:45], 0x440
	v_lshl_add_u64 v[74:75], v[74:75], 0, s[44:45]
	v_lshl_add_u64 v[78:79], v[78:79], 0, s[44:45]
	s_mov_b64 s[44:45], 0x20000
	s_waitcnt lgkmcnt(0)
	v_add_f32_e32 v46, v46, v47
	ds_bpermute_b32 v47, v122, v46
	s_add_i32 s0, s0, -1
	v_lshl_add_u64 v[76:77], v[76:77], 0, s[44:45]
	s_waitcnt lgkmcnt(0)
	v_add_f32_e32 v46, v46, v47
	v_fmac_f32_e32 v46, v103, v0
	v_mov_b32_e32 v103, v46
	s_mov_b32 s48, s50
